# v9: v6 + first per-unit barrier no longer drains vmcnt (Q loads and previous stores overlap the first tile DMA)
# speedup vs baseline: 1.0533x; 1.0007x over previous
; #define LAS __attribute__((address_space(3)))
; #define WAIT_BAR0() asm volatile("s_waitcnt vmcnt(0) lgkmcnt(0)\n\ts_barrier" ::: "memory")
; #define SB_DMA(T, st) do { const unsigned base_ = lds0 + (st) * 16384 + wid * 1024; glds16(ksrc + (size_t)(T) * 64 * 512, RFL(base_)); glds16(vsrc + (size_t)(T) * 4096, RFL(base_ + 8192)); } while (0)
; DI void sb_unit(LAS char* lds, int b, int h, int qb, const bf16_t* __restrict__ Q, const bf16_t* __restrict__ K, const bf16_t* __restrict__ VT, const bf16_t* __restrict__ G, bf16_t* __restrict__ MIX) {
;     int tid_ = threadIdx.x; asm volatile("" : "+v"(tid_));
;     const int tid = tid_, lane = tid & 63, r32 = lane & 31, hi = lane >> 5; const int wid = __builtin_amdgcn_readfirstlane(tid >> 6);
;     const int q0 = qb * 256, qw0 = q0 + 32 * wid, tq = qw0 + r32;
;     volatile LAS int* flags = (volatile LAS int*)(lds + MISC_OFF);
;     const unsigned lds0 = (unsigned)(uintptr_t)lds;
;     bf16x8 qf[4];
; #pragma unroll
;     for (int d0 = 0; d0 < 4; ++d0) qf[d0] = *(const bf16x8*)(Q + (size_t)(b * SEQ + tq) * 512 + h * 64 + d0 * 16 + hi * 8);
;     bf16x8 tp0, tp1, ones;
; #pragma unroll
;     for (int j = 0; j < 8; ++j) { const int kvk = 8 * (j >> 2) + 4 * hi + (j & 3); tp0[j] = (kvk > r32) ? (short)0x3F80 : (short)0; tp1[j] = (16 + kvk > r32) ? (short)0x3F80 : (short)0; ones[j] = (short)0x3F80; }
;     const int drow = 8 * wid + (lane >> 3), dch = (lane & 7) ^ ((drow >> 1) & 7);
;     const bf16_t* ksrc = K + (size_t)(b * SEQ + drow) * 512 + h * 64 + dch * 8;
;     const bf16_t* vsrc = VT + (size_t)(b * 8 + h) * (SEQ * 64) + drow * 64 + dch * 8;
;     ...
;     f32x16 o0 = splat16(0.f), o1 = splat16(0.f); float carry = 0.f; int done = 0;
;     const int nt = (q0 + 256) / 64;
;     WAIT_BAR0();
;     SB_DMA(nt - 1, 0);
;     for (int T = nt - 1, it = 0; T >= 0; --T, ++it) {
;         WAIT_BAR0();
;         if (it > 0) { volatile LAS int* fl = flags + ((it & 1) ^ 1) * 8; const int all = fl[0] & fl[1] & fl[2] & fl[3] & fl[4] & fl[5] & fl[6] & fl[7]; if (all) break; }
;         if (T > 0) SB_DMA(T - 1, (it + 1) & 1);
.LBB0_363:
	s_andn2_b64 vcc, exec, s[0:1]
	s_mov_b64 s[0:1], -1
	s_cbranch_vccz .LBB0_369
	v_mov_b32_e32 v35, v236
	s_lshl_b32 s4, s15, 8
	v_readfirstlane_b32 s0, v35
	s_ashr_i32 s27, s0, 6
	s_lshl_b32 s24, s27, 5
	v_bfe_u32 v0, v35, 3, 3
	v_and_b32_e32 v100, 31, v35
	s_add_i32 s24, s24, s4
	s_lshl_b32 s0, s14, 13
	v_lshl_or_b32 v6, s27, 3, v0
	v_or_b32_e32 v101, s24, v100
	v_add_u32_e32 v4, s0, v6
	v_add_u32_e32 v92, s0, v101
	v_ashrrev_i32_e32 v5, 31, v4
	v_readlane_b32 s0, v253, 4
	v_lshlrev_b64 v[4:5], 10, v[4:5]
	v_readlane_b32 s1, v253, 5
	v_lshrrev_b32_e32 v0, 1, v6
	s_lshl_b32 s98, s16, 7
	v_lshl_add_u64 v[4:5], s[0:1], 0, v[4:5]
	s_lshl_b32 s0, s14, 3
	v_xor_b32_e32 v0, v0, v35
	v_lshl_add_u64 v[4:5], v[4:5], 0, s[98:99]
	s_add_i32 s98, s0, s16
	s_lshl_b32 s23, s16, 6
	v_lshlrev_b32_e32 v0, 4, v0
	s_lshl_b64 s[0:1], s[98:99], 20
	v_readlane_b32 s6, v253, 14
	v_and_b32_e32 v0, 0x70, v0
	v_readlane_b32 s7, v253, 15
	s_add_u32 s0, s6, s0
	v_lshl_add_u64 v[96:97], v[4:5], 0, v[0:1]
	s_addc_u32 s1, s7, s1
	v_lshlrev_b32_e32 v4, 6, v6
	s_addk_i32 s4, 0x100
	v_ashrrev_i32_e32 v5, 31, v4
	s_ashr_i32 s38, s4, 6
	v_lshl_add_u64 v[4:5], v[4:5], 1, s[0:1]
	s_add_i32 s0, s38, -1
	s_ashr_i32 s1, s0, 31
	s_waitcnt lgkmcnt(0)
	s_barrier
	s_lshl_b32 s25, s27, 10
	s_lshl_b64 s[4:5], s[0:1], 16
	v_lshl_add_u64 v[98:99], v[4:5], 0, v[0:1]
	v_lshl_add_u64 v[4:5], v[96:97], 0, s[4:5]
	s_add_i32 s25, s25, 0
	s_mov_b32 s4, m0
	s_mov_b32 m0, s25
	s_nop 0
	global_load_lds_dwordx4 v[4:5], off
	s_mov_b32 m0, s4
	s_lshl_b64 s[4:5], s[0:1], 13
	v_bfe_u32 v2, v35, 5, 1
	v_lshl_add_u64 v[4:5], v[98:99], 0, s[4:5]
	s_add_i32 s1, s25, 0x2000
	s_mov_b32 s4, m0
	s_mov_b32 m0, s1
	s_nop 0
	global_load_lds_dwordx4 v[4:5], off
	s_mov_b32 m0, s4
	v_ashrrev_i32_e32 v93, 31, v92
	v_lshlrev_b32_e32 v3, 3, v2
	v_lshlrev_b64 v[94:95], 10, v[92:93]
	s_cmp_lt_i32 s38, 1
	v_lshlrev_b32_e32 v0, 1, v3
	s_cbranch_scc1 .LBB0_371
	v_readlane_b32 s4, v253, 2
	v_readlane_b32 s5, v253, 3
	s_lshl_b32 s98, s23, 1
	v_lshlrev_b32_e32 v102, 2, v2
	v_lshl_add_u64 v[4:5], s[4:5], 0, v[94:95]
	v_lshl_add_u64 v[4:5], v[4:5], 0, s[98:99]
	v_lshl_add_u64 v[4:5], v[4:5], 0, v[0:1]
	global_load_dwordx4 v[68:71], v[4:5], off
	global_load_dwordx4 v[72:75], v[4:5], off offset:32
	global_load_dwordx4 v[76:79], v[4:5], off offset:64
	global_load_dwordx4 v[80:83], v[4:5], off offset:96
	v_or_b32_e32 v3, 16, v102
	v_cmp_gt_u32_e32 vcc, v3, v100
	v_mov_b32_e32 v15, 0x3f80
	v_or_b32_e32 v5, 17, v102
	v_cndmask_b32_e32 v3, 0, v15, vcc
	v_or_b32_e32 v4, 18, v102
	v_cmp_gt_u32_e32 vcc, v5, v100
	v_or_b32_e32 v7, 19, v102
	v_or_b32_e32 v6, 24, v102
	v_cndmask_b32_e32 v5, 0, v15, vcc
	v_cmp_gt_u32_e32 vcc, v4, v100
	v_or_b32_e32 v8, 26, v102
	v_or_b32_e32 v9, 25, v102
	v_cndmask_b32_e32 v4, 0, v15, vcc
	v_cmp_gt_u32_e32 vcc, v7, v100
	v_or_b32_e32 v10, 27, v102
	s_mov_b32 s1, 0x5040100
	v_cndmask_b32_e32 v7, 0, v15, vcc
	v_cmp_gt_u32_e32 vcc, v6, v100
	v_or_b32_e32 v12, 10, v102
	v_or_b32_e32 v11, 11, v102
	v_cndmask_b32_e32 v6, 0, v15, vcc
	v_cmp_gt_u32_e32 vcc, v8, v100
	v_perm_b32 v88, v5, v3, s1
	s_add_i32 s98, s38, -2
	v_cndmask_b32_e32 v8, 0, v15, vcc
	v_cmp_gt_u32_e32 vcc, v9, v100
	s_waitcnt vmcnt(0) lgkmcnt(0)
	s_barrier
	s_lshl_b64 s[4:5], s[98:99], 16
	v_perm_b32 v89, v7, v4, s1
	v_cndmask_b32_e32 v9, 0, v15, vcc
	v_cmp_gt_u32_e32 vcc, v10, v100
	v_perm_b32 v90, v9, v6, s1
	s_or_b32 s26, s24, 31
	v_cndmask_b32_e32 v10, 0, v15, vcc
	v_cmp_gt_u32_e32 vcc, v102, v100
	v_perm_b32 v91, v10, v8, s1
	v_lshlrev_b32_e32 v103, 7, v100
	v_cndmask_b32_e32 v13, 0, v15, vcc
	v_cmp_lt_u32_e32 vcc, v102, v100
	s_nop 1
	v_cndmask_b32_e64 v14, v15, 0, vcc
	v_perm_b32 v84, v14, v13, s1
	v_or_b32_e32 v14, 2, v102
	v_or_b32_e32 v13, 3, v102
	v_cmp_gt_u32_e32 vcc, v14, v100
	s_nop 1
	v_cndmask_b32_e32 v14, 0, v15, vcc
	v_cmp_gt_u32_e32 vcc, v13, v100
	s_nop 1
	v_cndmask_b32_e32 v13, 0, v15, vcc
	v_perm_b32 v85, v13, v14, s1
	v_or_b32_e32 v14, 8, v102
	v_or_b32_e32 v13, 9, v102
	v_cmp_gt_u32_e32 vcc, v14, v100
	s_nop 1
	v_cndmask_b32_e32 v14, 0, v15, vcc
	v_cmp_gt_u32_e32 vcc, v13, v100
	s_nop 1
	v_cndmask_b32_e32 v13, 0, v15, vcc
	v_cmp_gt_u32_e32 vcc, v12, v100
	v_perm_b32 v86, v13, v14, s1
	s_nop 0
	v_cndmask_b32_e32 v12, 0, v15, vcc
	v_cmp_gt_u32_e32 vcc, v11, v100
	s_nop 1
	v_cndmask_b32_e32 v11, 0, v15, vcc
	v_perm_b32 v87, v11, v12, s1
	v_lshrrev_b32_e32 v11, 1, v35
	v_bfe_u32 v12, v35, 1, 3
	v_bitop3_b32 v3, v11, v2, 7 bitop3:0x6c
	v_lshlrev_b32_e32 v104, 4, v3
	v_bitop3_b32 v3, v2, v12, 2 bitop3:0x36
	v_lshlrev_b32_e32 v105, 4, v3
	v_bitop3_b32 v3, v2, v12, 4 bitop3:0x36
	v_bitop3_b32 v2, v2, v12, 6 bitop3:0x36
	v_lshlrev_b32_e32 v106, 4, v3
	v_lshlrev_b32_e32 v107, 4, v2
	v_lshl_add_u64 v[2:3], v[96:97], 0, s[4:5]
	s_add_i32 s1, s25, 0x4000
	s_mov_b32 s4, m0
	s_mov_b32 m0, s1
	s_nop 0
	global_load_lds_dwordx4 v[2:3], off
	s_mov_b32 m0, s4
	s_lshl_b64 s[4:5], s[98:99], 13
	v_lshl_add_u64 v[2:3], v[98:99], 0, s[4:5]
	s_add_i32 s1, s25, 0x6000
	s_lshl_b32 s4, s0, 6
	s_mov_b32 s0, m0
	s_mov_b32 m0, s1
	s_nop 0
	global_load_lds_dwordx4 v[2:3], off
	s_mov_b32 m0, s0
	s_cmp_ge_i32 s4, s26
	s_cbranch_scc1 .LBB0_413
; #define MFMA32(a, b, c) __builtin_amdgcn_mfma_f32_32x32x16_bf16((a), (b), (c), 0, 0, 0)
; DI int crow(int r, int hi) { return (r & 3) + 8 * (r >> 2) + 4 * hi; }
; DI float ex2(float x) { return __builtin_amdgcn_exp2f(x); }
; DI float lg2(float x) { return __builtin_amdgcn_logf(x); }
; DI void sb_unit(LAS char* lds, int b, int h, int qb, const bf16_t* __restrict__ Q, const bf16_t* __restrict__ K, const bf16_t* __restrict__ VT, const bf16_t* __restrict__ G, bf16_t* __restrict__ MIX) {
;     ...
;         if (kv0 < qw0 + 31 && !done) {
;             f32x16 p0 = splat16(0.f), p1 = splat16(0.f);
; #pragma unroll
;             for (int d0 = 0; d0 < 4; ++d0) { const bf16x8 k0 = ldsv(Kt + off128(r32, 2 * d0 + hi)), k1 = ldsv(Kt + off128(32 + r32, 2 * d0 + hi)); p0 = MFMA32(k0, qf[d0], p0); p1 = MFMA32(k1, qf[d0], p1); }
;             const bool diag = (kv0 + 63 >= qw0);
;             f32x16 L0, L1;
; #pragma unroll
;             for (int r = 0; r < 16; ++r) {
;                 { const float z = p0[r]; const float lg = (z > 30.f) ? z : lg2(1.0f + ex2(z)); const bool valid = !diag || (kv0 + crow(r, hi) < tq); L0[r] = valid ? -lg : 0.f; p0[r] = valid ? (z - lg) : -1e30f; }
;                 { const float z = p1[r]; const float lg = (z > 30.f) ? z : lg2(1.0f + ex2(z)); const bool valid = !diag || (kv0 + 32 + crow(r, hi) < tq); L1[r] = valid ? -lg : 0.f; p1[r] = valid ? (z - lg) : -1e30f; }
;             }
	v_add_u32_e32 v34, 0, v103
	v_add_u32_e32 v6, v34, v104
	ds_read_b128 v[2:5], v6
	ds_read_b128 v[6:9], v6 offset:4096
	v_add_u32_e32 v40, v34, v105
	ds_read_b128 v[36:39], v40
	ds_read_b128 v[40:43], v40 offset:4096
	s_or_b32 s0, s4, 63
	s_waitcnt vmcnt(3) lgkmcnt(3)
	v_mfma_f32_32x32x16_bf16 v[18:33], v[2:5], v[68:71], 0
	s_cmp_lt_i32 s0, s24
	s_cselect_b64 s[0:1], -1, 0
	s_waitcnt lgkmcnt(2)
	v_mfma_f32_32x32x16_bf16 v[2:17], v[6:9], v[68:71], 0
	s_waitcnt vmcnt(2) lgkmcnt(1)
	v_mfma_f32_32x32x16_bf16 v[18:33], v[36:39], v[72:75], v[18:33]
	s_waitcnt lgkmcnt(0)
	v_mfma_f32_32x32x16_bf16 v[2:17], v[40:43], v[72:75], v[2:17]
	v_add_u32_e32 v40, v34, v106
	ds_read_b128 v[36:39], v40
	ds_read_b128 v[40:43], v40 offset:4096
	v_add_u32_e32 v34, v34, v107
	s_waitcnt vmcnt(1) lgkmcnt(1)
	v_mfma_f32_32x32x16_bf16 v[18:33], v[36:39], v[76:79], v[18:33]
	s_waitcnt lgkmcnt(0)
	v_mfma_f32_32x32x16_bf16 v[2:17], v[40:43], v[76:79], v[2:17]
	ds_read_b128 v[36:39], v34
	ds_read_b128 v[40:43], v34 offset:4096
	s_waitcnt vmcnt(0) lgkmcnt(1)
	v_mfma_f32_32x32x16_bf16 v[18:33], v[36:39], v[80:83], v[18:33]
	s_waitcnt lgkmcnt(0)
	v_mfma_f32_32x32x16_bf16 v[2:17], v[40:43], v[80:83], v[2:17]
	s_nop 9
	v_exp_f32_e32 v34, v18
	v_or_b32_e32 v41, s4, v102
	v_cmp_lt_f32_e32 vcc, s22, v18
	v_or_b32_e32 v37, 32, v41
	v_add_f32_e32 v34, 1.0, v34
	v_log_f32_e32 v34, v34
	v_or_b32_e32 v61, 24, v41
	v_readlane_b32 s4, v254, 48
	v_readlane_b32 s6, v254, 50
	v_cndmask_b32_e32 v36, v34, v18, vcc
	v_cmp_lt_i32_e32 vcc, v41, v101
	s_or_b64 vcc, s[0:1], vcc
	v_sub_f32_e32 v18, v18, v36
	v_cndmask_b32_e64 v34, 0, -v36, vcc
	v_cndmask_b32_e32 v36, v237, v18, vcc
	v_exp_f32_e32 v18, v2
	v_cmp_lt_f32_e32 vcc, s22, v2
	v_readlane_b32 s7, v254, 51
	v_readlane_b32 s5, v254, 49
	v_add_f32_e32 v18, 1.0, v18
	v_log_f32_e32 v18, v18
	s_mov_b32 s6, s4
	s_mov_b32 s7, s4
	s_mov_b32 s5, s4
	v_cndmask_b32_e32 v38, v18, v2, vcc
	v_cmp_lt_i32_e32 vcc, v37, v101
	s_or_b64 vcc, s[0:1], vcc
	v_sub_f32_e32 v2, v2, v38
	v_cndmask_b32_e32 v37, v237, v2, vcc
	v_exp_f32_e32 v2, v19
	v_cndmask_b32_e64 v18, 0, -v38, vcc
	v_cmp_lt_f32_e32 vcc, s22, v19
	v_add_f32_e32 v2, 1.0, v2
	v_log_f32_e32 v2, v2
	s_nop 0
	v_cndmask_b32_e32 v38, v2, v19, vcc
	v_or_b32_e32 v2, 1, v41
	v_cmp_lt_i32_e32 vcc, v2, v101
	s_or_b64 vcc, s[0:1], vcc
	v_sub_f32_e32 v19, v19, v38
	v_cndmask_b32_e64 v2, 0, -v38, vcc
	v_cndmask_b32_e32 v38, v237, v19, vcc
	v_exp_f32_e32 v19, v3
	v_cmp_lt_f32_e32 vcc, s22, v3
	v_cvt_pk_bf16_f32 v2, v34, v2
	v_add_f32_e32 v19, 1.0, v19
	v_log_f32_e32 v19, v19
	s_nop 0
	v_cndmask_b32_e32 v39, v19, v3, vcc
	v_or_b32_e32 v19, 33, v41
	v_cmp_lt_i32_e32 vcc, v19, v101
	s_or_b64 vcc, s[0:1], vcc
	v_sub_f32_e32 v3, v3, v39
	v_cndmask_b32_e64 v19, 0, -v39, vcc
	v_cndmask_b32_e32 v39, v237, v3, vcc
	v_exp_f32_e32 v3, v20
	v_cmp_lt_f32_e32 vcc, s22, v20
	v_cvt_pk_bf16_f32 v18, v18, v19
	v_add_f32_e32 v3, 1.0, v3
	v_log_f32_e32 v3, v3
	s_nop 0
	v_cndmask_b32_e32 v40, v3, v20, vcc
	v_or_b32_e32 v3, 2, v41
	v_cmp_lt_i32_e32 vcc, v3, v101
	s_or_b64 vcc, s[0:1], vcc
	v_sub_f32_e32 v20, v20, v40
	v_cndmask_b32_e64 v3, 0, -v40, vcc
	v_cndmask_b32_e32 v40, v237, v20, vcc
	v_exp_f32_e32 v20, v4
	v_cmp_lt_f32_e32 vcc, s22, v4
	v_add_f32_e32 v20, 1.0, v20
	v_log_f32_e32 v20, v20
	s_nop 0
	v_cndmask_b32_e32 v42, v20, v4, vcc
	v_or_b32_e32 v20, 34, v41
	v_cmp_lt_i32_e32 vcc, v20, v101
	s_or_b64 vcc, s[0:1], vcc
	v_sub_f32_e32 v4, v4, v42
	v_cndmask_b32_e64 v20, 0, -v42, vcc
	v_cndmask_b32_e32 v42, v237, v4, vcc
	v_exp_f32_e32 v4, v21
	v_cmp_lt_f32_e32 vcc, s22, v21
	v_add_f32_e32 v4, 1.0, v4
	v_log_f32_e32 v4, v4
	s_nop 0
	v_cndmask_b32_e32 v43, v4, v21, vcc
	v_or_b32_e32 v4, 3, v41
	v_cmp_lt_i32_e32 vcc, v4, v101
	s_or_b64 vcc, s[0:1], vcc
	v_sub_f32_e32 v21, v21, v43
	v_cndmask_b32_e64 v4, 0, -v43, vcc
	v_cndmask_b32_e32 v43, v237, v21, vcc
	v_exp_f32_e32 v21, v5
	v_cmp_lt_f32_e32 vcc, s22, v5
	v_cvt_pk_bf16_f32 v3, v3, v4
	v_add_f32_e32 v21, 1.0, v21
	v_log_f32_e32 v21, v21
	s_nop 0
	v_cndmask_b32_e32 v44, v21, v5, vcc
	v_or_b32_e32 v21, 35, v41
	v_cmp_lt_i32_e32 vcc, v21, v101
	s_or_b64 vcc, s[0:1], vcc
	v_sub_f32_e32 v5, v5, v44
	v_cndmask_b32_e64 v21, 0, -v44, vcc
	v_cndmask_b32_e32 v44, v237, v5, vcc
	v_exp_f32_e32 v5, v22
	v_cmp_lt_f32_e32 vcc, s22, v22
	v_cvt_pk_bf16_f32 v19, v20, v21
	v_add_f32_e32 v5, 1.0, v5
	v_log_f32_e32 v5, v5
	s_nop 0
	v_cndmask_b32_e32 v45, v5, v22, vcc
	v_or_b32_e32 v5, 8, v41
	v_cmp_lt_i32_e32 vcc, v5, v101
	s_or_b64 vcc, s[0:1], vcc
	v_sub_f32_e32 v22, v22, v45
	v_cndmask_b32_e64 v5, 0, -v45, vcc
	v_cndmask_b32_e32 v45, v237, v22, vcc
	v_exp_f32_e32 v22, v6
	v_cmp_lt_f32_e32 vcc, s22, v6
	v_add_f32_e32 v22, 1.0, v22
	v_log_f32_e32 v22, v22
	s_nop 0
	v_cndmask_b32_e32 v46, v22, v6, vcc
	v_or_b32_e32 v22, 40, v41
	v_cmp_lt_i32_e32 vcc, v22, v101
	s_or_b64 vcc, s[0:1], vcc
	v_sub_f32_e32 v6, v6, v46
	v_cndmask_b32_e64 v22, 0, -v46, vcc
	v_cndmask_b32_e32 v46, v237, v6, vcc
	v_exp_f32_e32 v6, v23
	v_cmp_lt_f32_e32 vcc, s22, v23
	v_add_f32_e32 v6, 1.0, v6
	v_log_f32_e32 v6, v6
	s_nop 0
	v_cndmask_b32_e32 v47, v6, v23, vcc
	v_or_b32_e32 v6, 9, v41
	v_cmp_lt_i32_e32 vcc, v6, v101
	s_or_b64 vcc, s[0:1], vcc
	v_sub_f32_e32 v23, v23, v47
	v_cndmask_b32_e64 v6, 0, -v47, vcc
	v_cndmask_b32_e32 v47, v237, v23, vcc
	v_exp_f32_e32 v23, v7
	v_cmp_lt_f32_e32 vcc, s22, v7
	v_cvt_pk_bf16_f32 v4, v5, v6
	v_add_f32_e32 v23, 1.0, v23
	v_log_f32_e32 v23, v23
	s_nop 0
	v_cndmask_b32_e32 v48, v23, v7, vcc
	v_or_b32_e32 v23, 41, v41
	v_cmp_lt_i32_e32 vcc, v23, v101
	s_or_b64 vcc, s[0:1], vcc
	v_sub_f32_e32 v7, v7, v48
	v_cndmask_b32_e64 v23, 0, -v48, vcc
	v_cndmask_b32_e32 v48, v237, v7, vcc
	v_exp_f32_e32 v7, v24
; DI int crow(int r, int hi) { return (r & 3) + 8 * (r >> 2) + 4 * hi; }
; DI float ex2(float x) { return __builtin_amdgcn_exp2f(x); }
; DI float lg2(float x) { return __builtin_amdgcn_logf(x); }
; template <int S> DI bf16x8 pack8(const f32x16& x) { u32x4 p; p[0] = cvtpk(x[8 * S], x[8 * S + 1]); p[1] = cvtpk(x[8 * S + 2], x[8 * S + 3]); p[2] = cvtpk(x[8 * S + 4], x[8 * S + 5]); p[3] = cvtpk(x[8 * S + 6], x[8 * S + 7]); return __builtin_bit_cast(bf16x8, p); }
; DI void sb_unit(LAS char* lds, int b, int h, int qb, const bf16_t* __restrict__ Q, const bf16_t* __restrict__ K, const bf16_t* __restrict__ VT, const bf16_t* __restrict__ G, bf16_t* __restrict__ MIX) {
;     ...
;             for (int r = 0; r < 16; ++r) {
;                 { const float z = p0[r]; const float lg = (z > 30.f) ? z : lg2(1.0f + ex2(z)); const bool valid = !diag || (kv0 + crow(r, hi) < tq); L0[r] = valid ? -lg : 0.f; p0[r] = valid ? (z - lg) : -1e30f; }
;                 { const float z = p1[r]; const float lg = (z > 30.f) ? z : lg2(1.0f + ex2(z)); const bool valid = !diag || (kv0 + 32 + crow(r, hi) < tq); L1[r] = valid ? -lg : 0.f; p1[r] = valid ? (z - lg) : -1e30f; }
;             }
;             const bf16x8 Lh0 = pack8<0>(L0), Lh1 = pack8<1>(L0), Lh2 = pack8<0>(L1), Lh3 = pack8<1>(L1);
	v_cmp_lt_f32_e32 vcc, s22, v24
	v_cvt_pk_bf16_f32 v20, v22, v23
	v_add_f32_e32 v7, 1.0, v7
	v_log_f32_e32 v7, v7
	s_nop 0
	v_cndmask_b32_e32 v49, v7, v24, vcc
	v_or_b32_e32 v7, 10, v41
	v_cmp_lt_i32_e32 vcc, v7, v101
	s_or_b64 vcc, s[0:1], vcc
	v_sub_f32_e32 v24, v24, v49
	v_cndmask_b32_e64 v7, 0, -v49, vcc
	v_cndmask_b32_e32 v49, v237, v24, vcc
	v_exp_f32_e32 v24, v8
	v_cmp_lt_f32_e32 vcc, s22, v8
	v_add_f32_e32 v24, 1.0, v24
	v_log_f32_e32 v24, v24
	s_nop 0
	v_cndmask_b32_e32 v50, v24, v8, vcc
	v_or_b32_e32 v24, 42, v41
	v_cmp_lt_i32_e32 vcc, v24, v101
	s_or_b64 vcc, s[0:1], vcc
	v_sub_f32_e32 v8, v8, v50
	v_cndmask_b32_e64 v24, 0, -v50, vcc
	v_cndmask_b32_e32 v50, v237, v8, vcc
	v_exp_f32_e32 v8, v25
	v_cmp_lt_f32_e32 vcc, s22, v25
	v_add_f32_e32 v8, 1.0, v8
	v_log_f32_e32 v8, v8
	s_nop 0
	v_cndmask_b32_e32 v51, v8, v25, vcc
	v_or_b32_e32 v8, 11, v41
	v_cmp_lt_i32_e32 vcc, v8, v101
	s_or_b64 vcc, s[0:1], vcc
	v_sub_f32_e32 v25, v25, v51
	v_cndmask_b32_e64 v8, 0, -v51, vcc
	v_cndmask_b32_e32 v51, v237, v25, vcc
	v_exp_f32_e32 v25, v9
	v_cmp_lt_f32_e32 vcc, s22, v9
	v_cvt_pk_bf16_f32 v5, v7, v8
	v_add_f32_e32 v25, 1.0, v25
	v_log_f32_e32 v25, v25
	s_nop 0
	v_cndmask_b32_e32 v52, v25, v9, vcc
	v_or_b32_e32 v25, 43, v41
	v_cmp_lt_i32_e32 vcc, v25, v101
	s_or_b64 vcc, s[0:1], vcc
	v_sub_f32_e32 v9, v9, v52
	v_cndmask_b32_e64 v25, 0, -v52, vcc
	v_cndmask_b32_e32 v52, v237, v9, vcc
	v_exp_f32_e32 v9, v26
	v_cmp_lt_f32_e32 vcc, s22, v26
	v_cvt_pk_bf16_f32 v21, v24, v25
	v_mov_b64_e32 v[24:25], s[6:7]
	v_add_f32_e32 v9, 1.0, v9
	v_log_f32_e32 v9, v9
	v_mov_b64_e32 v[22:23], s[4:5]
	v_cndmask_b32_e32 v53, v9, v26, vcc
	v_or_b32_e32 v9, 16, v41
	v_cmp_lt_i32_e32 vcc, v9, v101
	s_or_b64 vcc, s[0:1], vcc
	v_sub_f32_e32 v26, v26, v53
	v_cndmask_b32_e64 v9, 0, -v53, vcc
	v_cndmask_b32_e32 v53, v237, v26, vcc
	v_exp_f32_e32 v26, v10
	v_cmp_lt_f32_e32 vcc, s22, v10
	v_add_f32_e32 v26, 1.0, v26
	v_log_f32_e32 v26, v26
	s_nop 0
	v_cndmask_b32_e32 v54, v26, v10, vcc
	v_or_b32_e32 v26, 48, v41
	v_cmp_lt_i32_e32 vcc, v26, v101
	s_or_b64 vcc, s[0:1], vcc
	v_sub_f32_e32 v10, v10, v54
	v_cndmask_b32_e64 v26, 0, -v54, vcc
	v_cndmask_b32_e32 v54, v237, v10, vcc
	v_exp_f32_e32 v10, v27
	v_cmp_lt_f32_e32 vcc, s22, v27
	v_add_f32_e32 v10, 1.0, v10
	v_log_f32_e32 v10, v10
	s_nop 0
	v_cndmask_b32_e32 v55, v10, v27, vcc
	v_or_b32_e32 v10, 17, v41
	v_cmp_lt_i32_e32 vcc, v10, v101
	s_or_b64 vcc, s[0:1], vcc
	v_sub_f32_e32 v27, v27, v55
	v_cndmask_b32_e64 v10, 0, -v55, vcc
	v_cndmask_b32_e32 v55, v237, v27, vcc
	v_exp_f32_e32 v27, v11
	v_cmp_lt_f32_e32 vcc, s22, v11
	v_add_f32_e32 v27, 1.0, v27
	v_log_f32_e32 v27, v27
	s_nop 0
	v_cndmask_b32_e32 v56, v27, v11, vcc
	v_or_b32_e32 v27, 49, v41
	v_cmp_lt_i32_e32 vcc, v27, v101
	s_or_b64 vcc, s[0:1], vcc
	v_sub_f32_e32 v11, v11, v56
	v_cndmask_b32_e64 v27, 0, -v56, vcc
	v_cndmask_b32_e32 v56, v237, v11, vcc
	v_exp_f32_e32 v11, v28
	v_cmp_lt_f32_e32 vcc, s22, v28
	v_cvt_pk_bf16_f32 v108, v26, v27
	v_add_f32_e32 v11, 1.0, v11
	v_log_f32_e32 v11, v11
	s_nop 0
	v_cndmask_b32_e32 v57, v11, v28, vcc
	v_or_b32_e32 v11, 18, v41
	v_cmp_lt_i32_e32 vcc, v11, v101
	s_or_b64 vcc, s[0:1], vcc
	v_sub_f32_e32 v28, v28, v57
	v_cndmask_b32_e64 v11, 0, -v57, vcc
	v_cndmask_b32_e32 v57, v237, v28, vcc
	v_exp_f32_e32 v28, v12
	v_cmp_lt_f32_e32 vcc, s22, v12
	v_add_f32_e32 v28, 1.0, v28
	v_log_f32_e32 v28, v28
	s_nop 0
	v_cndmask_b32_e32 v58, v28, v12, vcc
	v_or_b32_e32 v28, 50, v41
	v_cmp_lt_i32_e32 vcc, v28, v101
	s_or_b64 vcc, s[0:1], vcc
	v_sub_f32_e32 v12, v12, v58
	v_cndmask_b32_e64 v28, 0, -v58, vcc
	v_cndmask_b32_e32 v58, v237, v12, vcc
	v_exp_f32_e32 v12, v29
	v_cmp_lt_f32_e32 vcc, s22, v29
	v_add_f32_e32 v12, 1.0, v12
	v_log_f32_e32 v12, v12
	s_nop 0
	v_cndmask_b32_e32 v59, v12, v29, vcc
	v_or_b32_e32 v12, 19, v41
	v_cmp_lt_i32_e32 vcc, v12, v101
	s_or_b64 vcc, s[0:1], vcc
	v_sub_f32_e32 v29, v29, v59
	v_cndmask_b32_e64 v12, 0, -v59, vcc
	v_cndmask_b32_e32 v59, v237, v29, vcc
	v_exp_f32_e32 v29, v13
	v_cmp_lt_f32_e32 vcc, s22, v13
	v_add_f32_e32 v29, 1.0, v29
	v_log_f32_e32 v29, v29
	s_nop 0
	v_cndmask_b32_e32 v60, v29, v13, vcc
	v_or_b32_e32 v29, 51, v41
	v_cmp_lt_i32_e32 vcc, v29, v101
	s_or_b64 vcc, s[0:1], vcc
	v_sub_f32_e32 v13, v13, v60
	v_cndmask_b32_e64 v29, 0, -v60, vcc
	v_cndmask_b32_e32 v60, v237, v13, vcc
	v_exp_f32_e32 v13, v30
	v_cmp_lt_f32_e32 vcc, s22, v30
	v_cvt_pk_bf16_f32 v109, v28, v29
	v_add_f32_e32 v13, 1.0, v13
	v_log_f32_e32 v13, v13
	s_nop 0
	v_cndmask_b32_e32 v13, v13, v30, vcc
	v_cmp_lt_i32_e32 vcc, v61, v101
	s_or_b64 vcc, s[0:1], vcc
	s_nop 0
	v_cndmask_b32_e64 v66, 0, -v13, vcc
	v_sub_f32_e32 v13, v30, v13
	v_cndmask_b32_e32 v61, v237, v13, vcc
	v_exp_f32_e32 v13, v14
	v_cmp_lt_f32_e32 vcc, s22, v14
	v_or_b32_e32 v30, 56, v41
	v_add_f32_e32 v13, 1.0, v13
	v_log_f32_e32 v13, v13
	s_nop 0
	v_cndmask_b32_e32 v13, v13, v14, vcc
	v_cmp_lt_i32_e32 vcc, v30, v101
	s_or_b64 vcc, s[0:1], vcc
	v_or_b32_e32 v30, 57, v41
	v_cndmask_b32_e64 v67, 0, -v13, vcc
	v_sub_f32_e32 v13, v14, v13
	v_cndmask_b32_e32 v62, v237, v13, vcc
	v_exp_f32_e32 v13, v31
	v_cmp_lt_f32_e32 vcc, s22, v31
	v_or_b32_e32 v14, 25, v41
	v_add_f32_e32 v13, 1.0, v13
	v_log_f32_e32 v13, v13
	s_nop 0
	v_cndmask_b32_e32 v13, v13, v31, vcc
	v_cmp_lt_i32_e32 vcc, v14, v101
	s_or_b64 vcc, s[0:1], vcc
	s_nop 0
	v_cndmask_b32_e64 v14, 0, -v13, vcc
	v_sub_f32_e32 v13, v31, v13
	v_cndmask_b32_e32 v63, v237, v13, vcc
	v_exp_f32_e32 v13, v15
	v_cmp_lt_f32_e32 vcc, s22, v15
	v_cvt_pk_bf16_f32 v31, v11, v12
	v_add_f32_e32 v13, 1.0, v13
	v_log_f32_e32 v13, v13
	s_nop 0
	v_cndmask_b32_e32 v13, v13, v15, vcc
	v_cmp_lt_i32_e32 vcc, v30, v101
	s_or_b64 vcc, s[0:1], vcc
; #define MFMA32(a, b, c) __builtin_amdgcn_mfma_f32_32x32x16_bf16((a), (b), (c), 0, 0, 0)
; DI int crow(int r, int hi) { return (r & 3) + 8 * (r >> 2) + 4 * hi; }
; DI float ex2(float x) { return __builtin_amdgcn_exp2f(x); }
; DI float lg2(float x) { return __builtin_amdgcn_logf(x); }
; template <int S> DI bf16x8 pack8(const f32x16& x) { u32x4 p; p[0] = cvtpk(x[8 * S], x[8 * S + 1]); p[1] = cvtpk(x[8 * S + 2], x[8 * S + 3]); p[2] = cvtpk(x[8 * S + 4], x[8 * S + 5]); p[3] = cvtpk(x[8 * S + 6], x[8 * S + 7]); return __builtin_bit_cast(bf16x8, p); }
; #define SB_PV(ks, pa) { const bf16x8 v0 = ldsv(Vt + off128(r32, 2 * (ks) + hi)), v1 = ldsv(Vt + off128(32 + r32, 2 * (ks) + hi)); o0 = MFMA32(v0, pa, o0); o1 = MFMA32(v1, pa, o1); }
; DI void sb_unit(LAS char* lds, int b, int h, int qb, const bf16_t* __restrict__ Q, const bf16_t* __restrict__ K, const bf16_t* __restrict__ VT, const bf16_t* __restrict__ G, bf16_t* __restrict__ MIX) {
;     ...
;             for (int r = 0; r < 16; ++r) {
;                 { const float z = p0[r]; const float lg = (z > 30.f) ? z : lg2(1.0f + ex2(z)); const bool valid = !diag || (kv0 + crow(r, hi) < tq); L0[r] = valid ? -lg : 0.f; p0[r] = valid ? (z - lg) : -1e30f; }
;                 { const float z = p1[r]; const float lg = (z > 30.f) ? z : lg2(1.0f + ex2(z)); const bool valid = !diag || (kv0 + 32 + crow(r, hi) < tq); L1[r] = valid ? -lg : 0.f; p1[r] = valid ? (z - lg) : -1e30f; }
;             }
;             const bf16x8 Lh0 = pack8<0>(L0), Lh1 = pack8<1>(L0), Lh2 = pack8<0>(L1), Lh3 = pack8<1>(L1);
;             f32x16 C0 = splat16(carry), C1 = C0;
;             C0 = MFMA32(tp0, Lh0, C0); C0 = MFMA32(tp1, Lh1, C0); C0 = MFMA32(ones, Lh2, C0); C0 = MFMA32(ones, Lh3, C0);
;             C1 = MFMA32(tp0, Lh2, C1); C1 = MFMA32(tp1, Lh3, C1);
;             const float cn = C0[0] + L0[0];
;             carry = __shfl(cn, r32, 64);
; #pragma unroll
;             for (int r = 0; r < 16; ++r) { p0[r] = ex2(p0[r] + C0[r]); p1[r] = ex2(p1[r] + C1[r]); }
;             const bf16x8 pa0 = pack8<0>(p0), pa1 = pack8<1>(p0), pa2 = pack8<0>(p1), pa3 = pack8<1>(p1);
;     ...
;             SB_PV(0, pa0) SB_PV(1, pa1) SB_PV(2, pa2) SB_PV(3, pa3)
;     ...
;             done = __all(carry < -152.f) ? 1 : 0;
	v_or_b32_e32 v30, 58, v41
	v_cndmask_b32_e64 v110, 0, -v13, vcc
	v_sub_f32_e32 v13, v15, v13
	v_cndmask_b32_e32 v64, v237, v13, vcc
	v_exp_f32_e32 v13, v32
	v_cmp_lt_f32_e32 vcc, s22, v32
	v_or_b32_e32 v15, 26, v41
	v_cvt_pk_bf16_f32 v110, v67, v110
	v_add_f32_e32 v13, 1.0, v13
	v_log_f32_e32 v13, v13
	s_nop 0
	v_cndmask_b32_e32 v13, v13, v32, vcc
	v_cmp_lt_i32_e32 vcc, v15, v101
	s_or_b64 vcc, s[0:1], vcc
	s_nop 0
	v_cndmask_b32_e64 v15, 0, -v13, vcc
	v_sub_f32_e32 v13, v32, v13
	v_cndmask_b32_e32 v65, v237, v13, vcc
	v_exp_f32_e32 v13, v16
	v_cmp_lt_f32_e32 vcc, s22, v16
	v_cvt_pk_bf16_f32 v32, v66, v14
	v_add_f32_e32 v13, 1.0, v13
	v_log_f32_e32 v13, v13
	s_nop 0
	v_cndmask_b32_e32 v13, v13, v16, vcc
	v_cmp_lt_i32_e32 vcc, v30, v101
	s_or_b64 vcc, s[0:1], vcc
	v_or_b32_e32 v30, 59, v41
	v_cndmask_b32_e64 v111, 0, -v13, vcc
	v_sub_f32_e32 v13, v16, v13
	v_cndmask_b32_e32 v112, v237, v13, vcc
	v_exp_f32_e32 v13, v33
	v_cmp_lt_f32_e32 vcc, s22, v33
	v_or_b32_e32 v16, 27, v41
	v_add_f32_e32 v13, 1.0, v13
	v_log_f32_e32 v13, v13
	s_nop 0
	v_cndmask_b32_e32 v13, v13, v33, vcc
	v_cmp_lt_i32_e32 vcc, v16, v101
	s_or_b64 vcc, s[0:1], vcc
	s_nop 0
	v_cndmask_b32_e64 v16, 0, -v13, vcc
	v_sub_f32_e32 v13, v33, v13
	v_cndmask_b32_e32 v113, v237, v13, vcc
	v_exp_f32_e32 v13, v17
	v_cmp_lt_f32_e32 vcc, s22, v17
	v_cvt_pk_bf16_f32 v33, v15, v16
	v_add_f32_e32 v13, 1.0, v13
	v_log_f32_e32 v13, v13
	s_nop 0
	v_cndmask_b32_e32 v13, v13, v17, vcc
	v_cmp_lt_i32_e32 vcc, v30, v101
	s_or_b64 vcc, s[0:1], vcc
	v_cvt_pk_bf16_f32 v30, v9, v10
	v_cndmask_b32_e64 v41, 0, -v13, vcc
	v_sub_f32_e32 v13, v17, v13
	v_cndmask_b32_e32 v114, v237, v13, vcc
	v_mfma_f32_32x32x16_bf16 v[2:17], v[84:87], v[2:5], 0
	v_cvt_pk_bf16_f32 v111, v111, v41
	v_and_or_b32 v41, v238, 64, v100
	v_lshlrev_b32_e32 v41, 2, v41
	s_mov_b32 s0, s4
	v_writelane_b32 v254, s0, 48
	v_mfma_f32_32x32x16_bf16 v[2:17], v[88:91], v[30:33], v[2:17]
	s_nop 0
	v_writelane_b32 v254, s1, 49
	v_writelane_b32 v254, s2, 50
	v_writelane_b32 v254, s3, 51
	s_mov_b32 s0, 0xc3180000
	v_mfma_f32_32x32x16_bf16 v[2:17], v[22:25], v[18:21], v[2:17]
	v_mfma_f32_32x32x16_bf16 v[2:17], v[22:25], v[108:111], v[2:17]
	v_mfma_f32_32x32x16_bf16 v[18:33], v[84:87], v[18:21], 0
	s_nop 10
	v_add_f32_e32 v10, v10, v53
	v_add_f32_e32 v11, v11, v55
	v_add_f32_e32 v34, v34, v2
	v_add_f32_e32 v2, v2, v36
	v_add_f32_e32 v3, v3, v38
	v_add_f32_e32 v4, v4, v40
	v_add_f32_e32 v5, v5, v43
	v_mfma_f32_32x32x16_bf16 v[18:33], v[88:91], v[108:111], v[18:33]
	v_add_f32_e32 v6, v6, v45
	v_add_f32_e32 v7, v7, v47
	v_add_f32_e32 v8, v8, v49
	v_add_f32_e32 v9, v9, v51
	v_exp_f32_e32 v10, v10
	v_exp_f32_e32 v11, v11
	v_add_f32_e32 v12, v12, v57
	v_add_f32_e32 v13, v13, v59
	v_exp_f32_e32 v2, v2
	v_exp_f32_e32 v3, v3
	v_exp_f32_e32 v4, v4
	v_exp_f32_e32 v5, v5
	v_exp_f32_e32 v6, v6
	v_exp_f32_e32 v7, v7
	v_exp_f32_e32 v8, v8
	v_exp_f32_e32 v9, v9
	v_exp_f32_e32 v12, v12
	v_exp_f32_e32 v13, v13
	v_add_f32_e32 v21, v44, v21
	v_cvt_pk_bf16_f32 v44, v10, v11
	v_add3_u32 v10, 0, v104, v103
	v_add_f32_e32 v18, v37, v18
	v_add_f32_e32 v19, v39, v19
	v_add_f32_e32 v20, v42, v20
	v_add_f32_e32 v22, v46, v22
	v_add_f32_e32 v23, v48, v23
	v_add_f32_e32 v24, v50, v24
	v_add_f32_e32 v25, v52, v25
	v_add_f32_e32 v26, v54, v26
	v_add_f32_e32 v27, v56, v27
	v_add_f32_e32 v28, v58, v28
	v_add_f32_e32 v29, v60, v29
	v_add_f32_e32 v14, v14, v61
	v_add_f32_e32 v30, v62, v30
	v_add_f32_e32 v15, v15, v63
	v_add_f32_e32 v31, v64, v31
	v_add_f32_e32 v16, v16, v65
	v_add_f32_e32 v32, v112, v32
	v_add_f32_e32 v17, v17, v113
	v_add_f32_e32 v33, v114, v33
	v_cvt_pk_bf16_f32 v2, v2, v3
	v_cvt_pk_bf16_f32 v3, v4, v5
	v_cvt_pk_bf16_f32 v4, v6, v7
	v_cvt_pk_bf16_f32 v5, v8, v9
	v_cvt_pk_bf16_f32 v45, v12, v13
	ds_read_b128 v[6:9], v10 offset:8192
	ds_read_b128 v[10:13], v10 offset:12288
	v_exp_f32_e32 v18, v18
	v_exp_f32_e32 v19, v19
	v_exp_f32_e32 v20, v20
	v_exp_f32_e32 v21, v21
	v_exp_f32_e32 v22, v22
	v_exp_f32_e32 v23, v23
	v_exp_f32_e32 v24, v24
	v_exp_f32_e32 v25, v25
	v_exp_f32_e32 v26, v26
	v_exp_f32_e32 v27, v27
	v_exp_f32_e32 v28, v28
	v_exp_f32_e32 v29, v29
	v_exp_f32_e32 v14, v14
	v_exp_f32_e32 v30, v30
	v_exp_f32_e32 v15, v15
	v_exp_f32_e32 v31, v31
	v_exp_f32_e32 v16, v16
	v_exp_f32_e32 v32, v32
	v_exp_f32_e32 v17, v17
	v_exp_f32_e32 v33, v33
	ds_bpermute_b32 v34, v41, v34
	v_cvt_pk_bf16_f32 v46, v14, v15
	v_cvt_pk_bf16_f32 v47, v16, v17
	v_cvt_pk_bf16_f32 v40, v18, v19
	v_cvt_pk_bf16_f32 v41, v20, v21
	v_cvt_pk_bf16_f32 v42, v22, v23
	v_cvt_pk_bf16_f32 v43, v24, v25
	v_cvt_pk_bf16_f32 v36, v26, v27
	v_cvt_pk_bf16_f32 v37, v28, v29
	v_cvt_pk_bf16_f32 v38, v30, v31
	v_cvt_pk_bf16_f32 v39, v32, v33
	s_waitcnt lgkmcnt(2)
	v_mfma_f32_32x32x16_bf16 v[18:33], v[6:9], v[2:5], 0
	v_add3_u32 v52, 0, v105, v103
	ds_read_b128 v[48:51], v52 offset:8192
	ds_read_b128 v[52:55], v52 offset:12288
	s_waitcnt lgkmcnt(2)
	v_cmp_gt_f32_e32 vcc, s0, v34
	s_cmp_eq_u64 vcc, exec
	s_cselect_b64 s[0:1], -1, 0
	v_mfma_f32_32x32x16_bf16 v[2:17], v[10:13], v[2:5], 0
	s_waitcnt lgkmcnt(1)
	v_mfma_f32_32x32x16_bf16 v[18:33], v[48:51], v[44:47], v[18:33]
	v_add3_u32 v48, 0, v106, v103
	s_waitcnt lgkmcnt(0)
	v_mfma_f32_32x32x16_bf16 v[2:17], v[52:55], v[44:47], v[2:17]
	ds_read_b128 v[44:47], v48 offset:8192
	ds_read_b128 v[48:51], v48 offset:12288
	s_waitcnt lgkmcnt(1)
	v_mfma_f32_32x32x16_bf16 v[18:33], v[44:47], v[40:43], v[18:33]
	v_add3_u32 v44, 0, v107, v103
	s_waitcnt lgkmcnt(0)
	v_mfma_f32_32x32x16_bf16 v[2:17], v[48:51], v[40:43], v[2:17]
	ds_read_b128 v[40:43], v44 offset:8192
	ds_read_b128 v[44:47], v44 offset:12288
	s_waitcnt lgkmcnt(1)
	v_mfma_f32_32x32x16_bf16 v[18:33], v[40:43], v[36:39], v[18:33]
	s_waitcnt lgkmcnt(0)
	v_mfma_f32_32x32x16_bf16 v[2:17], v[44:47], v[36:39], v[2:17]
	v_cndmask_b32_e64 v36, 0, 1, s[0:1]
	s_branch .LBB0_414

; #define LAS __attribute__((address_space(3)))
; DI float ex2(float x) { return __builtin_amdgcn_exp2f(x); }
; #define WAIT_BAR0() asm volatile("s_waitcnt vmcnt(0) lgkmcnt(0)\n\ts_barrier" ::: "memory")
; DI void df_unit(LAS char* lds, int b, int h, int qb, const bf16_t* __restrict__ Q, const bf16_t* __restrict__ K, const bf16_t* __restrict__ VT, const bf16_t* __restrict__ G, bf16_t* __restrict__ MIX,
;                 float lam, float Mb  , const float* __restrict__ subg) {
;     int tid_ = threadIdx.x; asm volatile("" : "+v"(tid_));
;     const int tid = tid_, lane = tid & 63, r32 = lane & 31, hi = lane >> 5; const int wid = __builtin_amdgcn_readfirstlane(tid >> 6);
;     const int mp = wid >> 2, wq = wid & 3;
;     const int q0 = qb * 128, qw0 = q0 + 32 * wq, tq = qw0 + r32;
;     LAS float* Xch = (LAS float*)lds;
;     const unsigned lds0 = (unsigned)(uintptr_t)lds;
;     DfCtx c; c.qw0 = qw0; c.tq = 0; c.hi = 0;
; #pragma unroll
;     for (int d0 = 0; d0 < 4; ++d0) c.qf[d0] = *(const bf16x8*)(Q + (size_t)(b * SEQ + tq) * 512 + h * 128 + mp * 64 + d0 * 16 + hi * 8);
;     { const int kx = hi ^ (r32 & 15), vx = hi ^ ((r32 >> 1) & 7);
; #pragma unroll
;       for (int i = 0; i < 4; ++i) { c.kad[i] = r32 * 256 + (((8 * mp + 2 * i) ^ kx) << 4); c.vad[i] = r32 * 128 + (((2 * i) ^ vx) << 4); } }
;     const int krow = 4 * wid + (lane >> 4), kch = (lane & 15) ^ (krow & 15);
;     const int vrow = 8 * wid + (lane >> 3), vch = (lane & 7) ^ ((vrow >> 1) & 7);
;     const bf16_t* ksrc = K + (size_t)(b * SEQ + krow) * 512 + h * 128 + kch * 8;
;     const bf16_t* vsrc = VT + (size_t)(b * 4 + h) * (SEQ * 128) + vrow * 64 + vch * 8;
;     ...
;     f32x16 O[4];
; #pragma unroll
;     for (int i = 0; i < 4; ++i) O[i] = splat16(0.f);
;     float l = 0.f;
;     const float slope2 = ex2(-2.0f * (float)(h + 1)) * LOG2E;
;     c.sl = slope2; c.c0 = -slope2 * (float)(tq - 4 * hi) - Mb;
;     const int nt = (q0 + 128) / 64;
;     int T0 = 0; { float mb2 = Mb; asm volatile("" : "+s"(mb2)); const int W = (int)ceilf((150.0f + 2.0f * mb2) / slope2) + 1; const int x = q0 - 63 - W; if (x >= 0) T0 = x / 64 + 1; }
;     WAIT_BAR0();
;     DF_DMA(T0, 0, 0); if (T0 + 1 < nt) DF_DMA(T0 + 1, 16384, 16384);
.LBB0_373:
	v_mov_b32_e32 v42, v236
	s_lshl_b32 s45, s15, 7
	v_readfirstlane_b32 s0, v42
	s_ashr_i32 s4, s0, 6
	s_ashr_i32 s6, s0, 8
	v_writelane_b32 v255, s0, 18
	s_and_b32 s0, s4, 3
	s_lshl_b32 s61, s0, 5
	v_and_b32_e32 v41, 31, v42
	v_writelane_b32 v255, s0, 19
	s_or_b32 s0, s61, s45
	v_or_b32_e32 v44, s0, v41
	s_lshl_b32 s5, s14, 13
	v_add_u32_e32 v2, s5, v44
	v_writelane_b32 v255, s0, 20
	v_ashrrev_i32_e32 v3, 31, v2
	v_readlane_b32 s0, v253, 8
	v_lshlrev_b64 v[2:3], 10, v[2:3]
	v_readlane_b32 s1, v253, 9
	s_lshl_b32 s98, s16, 8
	v_bfe_u32 v43, v42, 5, 1
	v_lshl_add_u64 v[2:3], s[0:1], 0, v[2:3]
	s_lshl_b32 s0, s6, 6
	v_lshl_add_u64 v[2:3], v[2:3], 0, s[98:99]
	s_ashr_i32 s1, s0, 31
	v_lshl_add_u64 v[2:3], s[0:1], 1, v[2:3]
	v_lshlrev_b32_e32 v0, 4, v43
	v_lshl_add_u64 v[2:3], v[2:3], 0, v[0:1]
	global_load_dwordx4 v[130:133], v[2:3], off
	global_load_dwordx4 v[134:137], v[2:3], off offset:32
	global_load_dwordx4 v[138:141], v[2:3], off offset:64
	global_load_dwordx4 v[142:145], v[2:3], off offset:96
	v_bfe_u32 v39, v42, 3, 3
	v_writelane_b32 v255, s6, 21
	s_lshl_b32 s0, s4, 2
	v_bfe_u32 v250, v42, 4, 2
	v_lshl_or_b32 v4, s4, 3, v39
	v_or_b32_e32 v0, s0, v250
	v_writelane_b32 v255, s0, 22
	v_bitop3_b32 v38, s0, v42, v250 bitop3:0x36
	v_lshrrev_b32_e32 v2, 1, v4
	s_lshl_b32 s0, s14, 2
	v_xor_b32_e32 v40, v2, v42
	v_add_u32_e32 v2, s5, v0
	s_add_i32 s0, s0, s16
	s_mov_b32 s1, s99
	v_ashrrev_i32_e32 v3, 31, v2
	s_lshl_b64 s[6:7], s[0:1], 21
	v_readlane_b32 s0, v253, 10
	v_lshlrev_b64 v[2:3], 10, v[2:3]
	v_readlane_b32 s1, v253, 11
	v_writelane_b32 v255, s5, 23
	v_lshlrev_b32_e32 v4, 6, v4
	v_lshl_add_u64 v[2:3], s[0:1], 0, v[2:3]
	v_readlane_b32 s0, v253, 16
	v_readlane_b32 s1, v253, 17
	s_add_u32 s0, s0, s6
	v_ashrrev_i32_e32 v5, 31, v4
	v_writelane_b32 v255, s6, 24
	s_addc_u32 s1, s1, s7
	v_lshlrev_b32_e32 v0, 4, v38
	v_writelane_b32 v255, s7, 25
	v_lshl_add_u64 v[4:5], v[4:5], 1, s[0:1]
	s_mov_b32 s0, s16
	v_lshl_add_u64 v[2:3], v[2:3], 0, s[98:99]
	v_and_b32_e32 v0, 0xf0, v0
	v_writelane_b32 v255, s0, 26
	v_lshl_add_u64 v[2:3], v[2:3], 0, v[0:1]
	v_lshlrev_b32_e32 v0, 4, v40
	v_writelane_b32 v255, s1, 27
	s_not_b32 s0, s16
	v_and_b32_e32 v0, 0x70, v0
	s_lshl_b32 s0, s0, 1
	v_lshl_add_u64 v[4:5], v[4:5], 0, v[0:1]
	v_cvt_f32_i32_e32 v0, s0
	s_add_i32 s0, s45, 0x80
	s_ashr_i32 s23, s0, 6
	v_readlane_b32 s0, v254, 63
	v_exp_f32_e32 v7, v0
	s_waitcnt lgkmcnt(0)
	s_barrier
	s_nop 0
	v_mov_b32_e32 v6, s0
	v_readlane_b32 s0, v254, 52
	v_readlane_b32 s1, v254, 53
	s_mov_b32 s0, s8
	s_mov_b32 s5, s1
	v_pk_mul_f32 v[178:179], v[6:7], s[0:1]
	v_writelane_b32 v254, s4, 52
	v_add_f32_e32 v0, 0x43160000, v178
	v_div_scale_f32 v6, s[0:1], v179, v179, v0
	v_rcp_f32_e32 v7, v6
	v_writelane_b32 v254, s5, 53
	v_fma_f32 v8, -v6, v7, 1.0
	v_fmac_f32_e32 v7, v8, v7
	v_div_scale_f32 v8, vcc, v0, v179, v0
	v_mul_f32_e32 v9, v8, v7
	v_fma_f32 v10, -v6, v9, v8
	v_fmac_f32_e32 v9, v10, v7
	v_fma_f32 v6, -v6, v9, v8
	v_div_fmas_f32 v6, v6, v7, v9
	v_div_fixup_f32 v0, v6, v179, v0
	v_ceil_f32_e32 v0, v0
	v_cvt_i32_f32_e32 v0, v0
	s_nop 0
	v_readfirstlane_b32 s0, v0
	s_not_b32 s0, s0
	s_add_i32 s0, s45, s0
	s_sub_i32 s0, s0, 63
	s_lshr_b32 s1, s0, 6
	s_add_i32 s1, s1, 1
	s_cmp_gt_i32 s0, -1
	s_cselect_b32 s98, s1, 0
	s_lshl_b32 s6, s4, 10
	s_lshl_b64 s[24:25], s[98:99], 16
	s_add_i32 s5, s6, 0
	v_lshl_add_u64 v[6:7], v[2:3], 0, s[24:25]
	s_mov_b32 s0, m0
	s_mov_b32 m0, s5
	s_nop 0
	global_load_lds_dwordx4 v[6:7], off
	s_mov_b32 m0, s0
	s_mov_b64 s[0:1], 0x8000
	s_lshl_b64 s[26:27], s[98:99], 14
	v_lshl_add_u64 v[6:7], v[6:7], 0, s[0:1]
	s_add_i32 s7, s5, 0x2000
	s_mov_b32 s0, m0
	s_mov_b32 m0, s7
	s_nop 0
	global_load_lds_dwordx4 v[6:7], off
	s_mov_b32 m0, s0
	s_add_i32 s14, s5, 0x10000
	v_lshl_add_u64 v[8:9], v[4:5], 0, s[26:27]
	s_mov_b32 s0, m0
	s_mov_b32 m0, s14
	s_nop 0
	global_load_lds_dwordx4 v[8:9], off
	s_mov_b32 m0, s0
	s_mov_b64 s[0:1], 0x2000
	v_lshl_add_u64 v[6:7], v[8:9], 0, s[0:1]
	s_add_i32 s44, s5, 0x12000
	s_mov_b32 s0, m0
	s_mov_b32 m0, s44
	s_nop 0
	global_load_lds_dwordx4 v[6:7], off
	s_mov_b32 m0, s0
	s_add_i32 s60, s98, 1
	s_mov_b64 s[0:1], -1
	s_cmp_ge_i32 s60, s23
	s_cbranch_scc0 .LBB0_382
	s_waitcnt vmcnt(0) lgkmcnt(0)
	s_barrier
	s_cbranch_execz .LBB0_383
